# attnA: K rows loaded coalesced (8 lanes per 128-B row, same addresses as V at -1536 B) and turned into MFMA fragments through the per-wave LDS stage, instead of 4-rows-per-quad fragment loads from glo
# baseline (speedup 1.0000x reference)
; #define GAS __attribute__((address_space(1)))
; #define LAS __attribute__((address_space(3)))
; __device__ __forceinline__ void attnA_unit(const Ctx& C, int unit) {
;     ...
;     const int lane = C.lane, i16 = lane & 15, g = lane >> 4;
;     { const GAS float* TA = (const GAS float*)(C.ws + WS_TABA);
;       for (int idx = C.tid; idx < 3 * 176; idx += 512) { const int grp = idx / 176, e = idx % 176 - 16; biasT[idx] = (e >= 0 && e <= 128) ? TA[(grp * 4 + j) * 132 + e] : 0.f; } }
;     __syncthreads();
;     const int L = i16 + 144 - 8 * g;
; #pragma unroll 1
;     for (int it = C.wave; it < 48; it += 8) {
;         const int grp = it >> 4, k = it & 15;
;         int dl, r, i0;
;         if (grp == 0) { dl = 1; r = 0; i0 = T0 + 16 * k; } else if (grp == 1) { dl = 4; r = k & 3; i0 = (T0 >> 2) + 16 * (k >> 2); } else { dl = 16; r = k; i0 = T0 >> 4; }
;         const int head = 4 * grp + j;
;         const unsigned rstride = (unsigned)dl * (ZC * 2), rbase = (unsigned)r * (ZC * 2);
;         const int tq = r + dl * (i0 + i16);
;         const unsigned qoff = (unsigned)tq * (ZC * 2) + (QA + head * 64 + 8 * g) * 2;
;         const bf16x8 q0 = *(const GAS bf16x8*)(Zg + qoff), q1 = *(const GAS bf16x8*)(Zg + qoff + 64);
;         const int kbase = i0 - 144;
;         const int klane = kbase + 8 * (i16 >> 2) + (i16 & 3);
;         const unsigned kcol = rbase + (KA + head * 64 + 8 * g) * 2;
;     ...
;         const LAS unsigned char* vrd = Vst + (8 * g + (i16 >> 2)) * 144 + 8 * (i16 & 3);
;         LAS unsigned char* vwr = Vst + (lane >> 3) * 144 + (lane & 7) * 16;
.LBB0_557:
	s_or_b64 exec, exec, s[38:39]
	s_lshl_b32 s19, s74, 8
	s_ashr_i32 s21, s74, 6
	s_and_b32 s19, s19, 0xf00
	s_cmp_gt_i32 s72, 47
	s_mov_b32 s0, 0x800000
	s_mov_b32 s1, 0x3f317217
	s_movk_i32 s6, 0xff7c
	s_waitcnt lgkmcnt(0)
	s_barrier
	s_cbranch_scc1 .LBB0_569
	v_and_b32_e32 v5, 64, v228
	s_mul_i32 s23, s21, 0x2600000
	v_xor_b32_e32 v4, 16, v228
	v_add_u32_e32 v5, 64, v5
	s_mul_hi_i32 s22, s21, 0x2600000
	s_add_u32 s23, s64, s23
	v_cmp_lt_i32_e32 vcc, v4, v5
	s_addc_u32 s22, s65, s22
	s_add_u32 s66, s23, 0xbc00000
	v_cndmask_b32_e32 v4, v228, v4, vcc
	v_lshlrev_b32_e32 v141, 2, v4
	v_xor_b32_e32 v4, 32, v228
	v_and_b32_e32 v133, 15, v132
	v_lshrrev_b32_e32 v1, 1, v132
	s_addc_u32 s67, s22, 0
	s_mul_i32 s22, s72, 0x1200
	v_cmp_lt_i32_e32 vcc, v4, v5
	v_or_b32_e32 v0, 0x90, v133
	v_and_b32_e32 v134, 24, v1
	s_add_i32 s24, s22, 0
	v_cndmask_b32_e32 v4, v228, v4, vcc
	v_sub_u32_e32 v0, v0, v134
	v_lshlrev_b32_e32 v142, 2, v4
	v_mov_b32_e32 v4, s24
	s_movk_i32 s24, 0x83
	v_cmp_gt_u32_e64 s[40:41], s24, v0
	s_movk_i32 s24, 0x82
	v_cmp_gt_u32_e64 s[42:43], s24, v0
	s_movk_i32 s24, 0x85
	v_cmp_gt_u32_e64 s[44:45], s24, v0
	s_movk_i32 s24, 0x84
	v_cmp_gt_u32_e64 s[46:47], s24, v0
	s_movk_i32 s24, 0x87
	v_sub_u32_e32 v1, v133, v134
	v_cmp_gt_u32_e64 s[48:49], s24, v0
	s_movk_i32 s24, 0x86
	v_lshl_add_u32 v135, v1, 2, 0
	v_bfe_u32 v1, v132, 2, 2
	v_and_b32_e32 v2, 3, v132
	v_cmp_gt_u32_e64 s[50:51], s24, v0
	s_movk_i32 s24, 0x88
	v_lshl_or_b32 v138, v1, 3, v2
	v_lshrrev_b32_e32 v139, 3, v169
	v_lshlrev_b32_e32 v3, 4, v169
	v_or_b32_e32 v1, v134, v1
	s_movk_i32 s7, 0x90
	v_cmp_gt_u32_e64 s[52:53], s24, v0
	s_movk_i32 s24, 0x80
	v_and_b32_e32 v3, 0x70, v3
	v_mad_u32_u24 v1, v1, s7, v4
	v_lshlrev_b32_e32 v2, 3, v2
	v_mad_u32_u24 v4, v139, s7, v4
	v_cmp_gt_u32_e64 s[54:55], s24, v0
	s_lshl_b32 s24, s72, 4
	v_add_u32_e32 v136, 0, v134
	s_lshr_b32 s22, s19, 4
	s_lshr_b32 s23, s19, 2
	s_lshl_b32 s36, s20, 6
	v_or_b32_e32 v137, 0x300, v134
	v_or_b32_e32 v140, 0xc00, v3
	v_cmp_gt_u32_e32 vcc, 16, v169
	s_bfe_u32 s70, s73, 0x20006
	v_cmp_gt_u32_e64 s[38:39], s16, v0
	s_lshl_b32 s71, s72, 2
	s_add_i32 s73, s19, s24
	v_add_u32_e32 v143, v4, v3
	v_add_u32_e32 v144, v1, v2
	v_bfe_u32 v206, v169, 5, 1
	v_mul_u32_u24_e32 v206, 0x6c0, v206
	v_add_u32_e32 v206, v143, v206
	v_and_b32_e32 v207, 7, v169
	v_lshlrev_b32_e32 v207, 4, v207
	v_sub_u32_e32 v207, v143, v207
	v_mul_u32_u24_e32 v208, 0x90, v139
	v_sub_u32_e32 v207, v207, v208
	v_mul_u32_u24_e32 v208, 0x90, v133
	v_add_u32_e32 v207, v207, v208
	v_lshl_add_u32 v207, v134, 1, v207
	s_branch .LBB0_560

; #define GAS __attribute__((address_space(1)))
; __device__ __forceinline__ void attnA_unit(const Ctx& C, int unit) {
;     ...
;         const int tq = r + dl * (i0 + i16);
;         const unsigned qoff = (unsigned)tq * (ZC * 2) + (QA + head * 64 + 8 * g) * 2;
;         const bf16x8 q0 = *(const GAS bf16x8*)(Zg + qoff), q1 = *(const GAS bf16x8*)(Zg + qoff + 64);
;         const int kbase = i0 - 144;
;         const int klane = kbase + 8 * (i16 >> 2) + (i16 & 3);
;         const unsigned kcol = rbase + (KA + head * 64 + 8 * g) * 2;
;         bf16x8 kf[10][2];
; #pragma unroll
;         for (int kt = 0; kt < 10; ++kt) { int ks = klane + 32 * (kt >> 1) + 4 * (kt & 1); ks = ks < 0 ? 0 : ks;
;             const unsigned off = (unsigned)ks * rstride + kcol; kf[kt][0] = *(const GAS bf16x8*)(Zg + off); kf[kt][1] = *(const GAS bf16x8*)(Zg + off + 64); }
;         v4u vreg[5][4];
;         { const int vl = kbase + (lane >> 3); const unsigned vcol = rbase + (VA + head * 64 + (lane & 7) * 8) * 2;
; #pragma unroll
;           for (int s5 = 0; s5 < 5; ++s5)
; #pragma unroll
;             for (int i = 0; i < 4; ++i) { int ks = vl + 32 * s5 + 8 * i; ks = ks < 0 ? 0 : ks; vreg[s5][i] = *(const GAS v4u*)(Zg + (unsigned)ks * rstride + vcol); } }
.LBB0_565:
	v_add_u32_e32 v0, s24, v133
	v_mul_lo_u32 v0, s25, v0
	s_lshl_b32 s68, s26, 8
	v_add_u32_e32 v145, s56, v0
	s_or_b32 s31, s68, s36
	v_mul_lo_u32 v0, v145, s33
	v_or_b32_e32 v1, s31, v134
	s_mul_i32 s27, s25, 0x2600
	v_lshl_add_u32 v0, v1, 1, v0
	s_add_i32 s25, s24, 0xffffff70
	s_mul_i32 s30, s56, 0x2600
	global_load_dwordx4 v[84:87], v0, s[66:67]
	global_load_dwordx4 v[80:83], v0, s[66:67] offset:64
	s_lshl_b32 s28, s31, 1
	v_add_u32_e32 v12, s25, v139
	s_add_i32 s30, s30, s28
	v_add_u32_e32 v192, s30, v140
	v_lshl_add_u64 v[8:9], s[66:67], 0, v[192:193]
	v_max_i32_e32 v0, 0, v12
	v_mul_lo_u32 v192, v0, s27
	v_lshl_add_u64 v[0:1], v[8:9], 0, v[192:193]
	global_load_dwordx4 v[146:149], v[0:1], off offset:-1536
	v_max_i32_e32 v2, -8, v12
	v_add_u32_e32 v2, 8, v2
	v_mul_lo_u32 v192, v2, s27
	v_lshl_add_u64 v[2:3], v[8:9], 0, v[192:193]
	global_load_dwordx4 v[150:153], v[2:3], off offset:-1536
	v_max_i32_e32 v0, -16, v12
	v_add_u32_e32 v0, 16, v0
	v_mul_lo_u32 v192, v0, s27
	v_lshl_add_u64 v[0:1], v[8:9], 0, v[192:193]
	global_load_dwordx4 v[154:157], v[0:1], off offset:-1536
	v_max_i32_e32 v2, -24, v12
	v_add_u32_e32 v2, 24, v2
	v_mul_lo_u32 v192, v2, s27
	v_lshl_add_u64 v[2:3], v[8:9], 0, v[192:193]
	global_load_dwordx4 v[158:161], v[2:3], off offset:-1536
	v_max_i32_e32 v0, -32, v12
	v_add_u32_e32 v0, 32, v0
	v_mul_lo_u32 v192, v0, s27
	v_lshl_add_u64 v[0:1], v[8:9], 0, v[192:193]
	global_load_dwordx4 v[162:165], v[0:1], off offset:-1536
	v_max_i32_e32 v2, -40, v12
	v_add_u32_e32 v2, 40, v2
	v_mul_lo_u32 v192, v2, s27
	v_lshl_add_u64 v[2:3], v[8:9], 0, v[192:193]
	global_load_dwordx4 v[166:169], v[2:3], off offset:-1536
	v_max_i32_e32 v0, -48, v12
	v_add_u32_e32 v0, 48, v0
	v_mul_lo_u32 v192, v0, s27
	v_lshl_add_u64 v[0:1], v[8:9], 0, v[192:193]
	global_load_dwordx4 v[170:173], v[0:1], off offset:-1536
	v_max_i32_e32 v2, -56, v12
	v_add_u32_e32 v2, 56, v2
	v_mul_lo_u32 v192, v2, s27
	v_lshl_add_u64 v[2:3], v[8:9], 0, v[192:193]
	global_load_dwordx4 v[174:177], v[2:3], off offset:-1536
	v_max_i32_e32 v0, -64, v12
	v_add_u32_e32 v0, 64, v0
	v_mul_lo_u32 v192, v0, s27
	v_lshl_add_u64 v[0:1], v[8:9], 0, v[192:193]
	global_load_dwordx4 v[178:181], v[0:1], off offset:-1536
	v_max_i32_e32 v2, -72, v12
	v_add_u32_e32 v2, 72, v2
	v_mul_lo_u32 v192, v2, s27
	v_lshl_add_u64 v[2:3], v[8:9], 0, v[192:193]
	global_load_dwordx4 v[128:131], v[2:3], off offset:-1536
	v_max_i32_e32 v0, -80, v12
	v_add_u32_e32 v0, 80, v0
	v_mul_lo_u32 v192, v0, s27
	v_lshl_add_u64 v[0:1], v[8:9], 0, v[192:193]
	global_load_dwordx4 v[124:127], v[0:1], off offset:-1536
	v_max_i32_e32 v2, -88, v12
	v_add_u32_e32 v2, 88, v2
	v_mul_lo_u32 v192, v2, s27
	v_lshl_add_u64 v[2:3], v[8:9], 0, v[192:193]
	global_load_dwordx4 v[120:123], v[2:3], off offset:-1536
	v_max_i32_e32 v0, -96, v12
	v_add_u32_e32 v0, 96, v0
	v_mul_lo_u32 v192, v0, s27
	v_lshl_add_u64 v[0:1], v[8:9], 0, v[192:193]
	global_load_dwordx4 v[116:119], v[0:1], off offset:-1536
	v_max_i32_e32 v2, -104, v12
	v_add_u32_e32 v2, 104, v2
	v_mul_lo_u32 v192, v2, s27
	v_lshl_add_u64 v[2:3], v[8:9], 0, v[192:193]
	global_load_dwordx4 v[112:115], v[2:3], off offset:-1536
	v_max_i32_e32 v0, -112, v12
	v_add_u32_e32 v0, 112, v0
	v_mul_lo_u32 v192, v0, s27
	v_lshl_add_u64 v[0:1], v[8:9], 0, v[192:193]
	global_load_dwordx4 v[108:111], v[0:1], off offset:-1536
	v_max_i32_e32 v2, -120, v12
	v_add_u32_e32 v2, 120, v2
	v_mul_lo_u32 v192, v2, s27
	v_lshl_add_u64 v[2:3], v[8:9], 0, v[192:193]
	global_load_dwordx4 v[100:103], v[2:3], off offset:-1536
	v_max_i32_e32 v0, -128, v12
	v_add_u32_e32 v0, 128, v0
	v_mul_lo_u32 v192, v0, s27
	v_lshl_add_u64 v[0:1], v[8:9], 0, v[192:193]
	global_load_dwordx4 v[104:107], v[0:1], off offset:-1536
	v_max_i32_e32 v2, -136, v12
	v_add_u32_e32 v2, 136, v2
	v_mul_lo_u32 v192, v2, s27
	v_lshl_add_u64 v[2:3], v[8:9], 0, v[192:193]
	global_load_dwordx4 v[96:99], v[2:3], off offset:-1536
	v_max_i32_e32 v0, -144, v12
	v_add_u32_e32 v0, 144, v0
	v_mul_lo_u32 v192, v0, s27
	v_lshl_add_u64 v[0:1], v[8:9], 0, v[192:193]
	global_load_dwordx4 v[92:95], v[0:1], off offset:-1536
	v_max_i32_e32 v2, -152, v12
	v_add_u32_e32 v2, 152, v2
	v_mul_lo_u32 v192, v2, s27
	v_lshl_add_u64 v[2:3], v[8:9], 0, v[192:193]
	global_load_dwordx4 v[88:91], v[2:3], off offset:-1536
	v_add_u32_e32 v192, s30, v140
	v_max_i32_e32 v0, 0, v12
	v_max_i32_e32 v2, -8, v12
	v_lshl_add_u64 v[8:9], s[66:67], 0, v[192:193]
	v_mul_lo_u32 v192, v0, s27
	v_add_u32_e32 v2, 8, v2
	v_lshl_add_u64 v[0:1], v[8:9], 0, v[192:193]
	v_mul_lo_u32 v192, v2, s27
	v_lshl_add_u64 v[2:3], v[8:9], 0, v[192:193]
	global_load_dwordx4 v[64:67], v[0:1], off
	global_load_dwordx4 v[68:71], v[2:3], off
	v_max_i32_e32 v0, -16, v12
	v_add_u32_e32 v0, 16, v0
	v_max_i32_e32 v2, 0xffffffe8, v12
	v_mul_lo_u32 v192, v0, s27
	v_add_u32_e32 v2, 24, v2
	v_lshl_add_u64 v[0:1], v[8:9], 0, v[192:193]
	v_mul_lo_u32 v192, v2, s27
	v_lshl_add_u64 v[2:3], v[8:9], 0, v[192:193]
	global_load_dwordx4 v[72:75], v[0:1], off
	global_load_dwordx4 v[76:79], v[2:3], off
	v_max_i32_e32 v0, 0xffffffe0, v12
	v_add_u32_e32 v0, 32, v0
	v_max_i32_e32 v2, 0xffffffd8, v12
	v_mul_lo_u32 v192, v0, s27
	v_add_u32_e32 v2, 40, v2
	v_lshl_add_u64 v[0:1], v[8:9], 0, v[192:193]
	v_mul_lo_u32 v192, v2, s27
	v_lshl_add_u64 v[2:3], v[8:9], 0, v[192:193]
	global_load_dwordx4 v[48:51], v[0:1], off
	global_load_dwordx4 v[52:55], v[2:3], off
	v_max_i32_e32 v0, 0xffffffd0, v12
	v_add_u32_e32 v0, 48, v0
	v_max_i32_e32 v2, 0xffffffc8, v12
	v_mul_lo_u32 v192, v0, s27
	v_add_u32_e32 v2, 56, v2
	v_lshl_add_u64 v[0:1], v[8:9], 0, v[192:193]
	v_mul_lo_u32 v192, v2, s27
	v_lshl_add_u64 v[2:3], v[8:9], 0, v[192:193]
; #define GAS __attribute__((address_space(1)))
; #define LAS __attribute__((address_space(3)))
; __device__ __forceinline__ f32x4 mfma16(bf16x8 a, bf16x8 b, f32x4 c) { return __builtin_amdgcn_mfma_f32_16x16x32_bf16(a, b, c, 0, 0, 0); }
; #define SBAR() __builtin_amdgcn_sched_barrier(0)
; #define SBAR() __builtin_amdgcn_sched_barrier(0)
; __device__ __forceinline__ void attnA_unit(const Ctx& C, int unit) {
;     ...
;         bf16x8 kf[10][2];
; #pragma unroll
;         for (int kt = 0; kt < 10; ++kt) { int ks = klane + 32 * (kt >> 1) + 4 * (kt & 1); ks = ks < 0 ? 0 : ks;
;             const unsigned off = (unsigned)ks * rstride + kcol; kf[kt][0] = *(const GAS bf16x8*)(Zg + off); kf[kt][1] = *(const GAS bf16x8*)(Zg + off + 64); }
;         v4u vreg[5][4];
;         { const int vl = kbase + (lane >> 3); const unsigned vcol = rbase + (VA + head * 64 + (lane & 7) * 8) * 2;
; #pragma unroll
;           for (int s5 = 0; s5 < 5; ++s5)
; #pragma unroll
;             for (int i = 0; i < 4; ++i) { int ks = vl + 32 * s5 + 8 * i; ks = ks < 0 ? 0 : ks; vreg[s5][i] = *(const GAS v4u*)(Zg + (unsigned)ks * rstride + vcol); } }
;         SBAR();
;         f32x4 S[10];
; #pragma unroll
;         for (int kt = 0; kt < 10; ++kt) { f32x4 a = mfma16(kf[kt][0], q0, (f32x4){0.f, 0.f, 0.f, 0.f}); S[kt] = mfma16(kf[kt][1], q1, a); }
;         const LAS float* tb = biasT + grp * 176 + 16 + L - 159;
;         const int kneg = kbase + 8 * g;
;         const bool anyneg = kbase < 0;
;         float tv[40];
; #pragma unroll
;         for (int kt = 0; kt < 10; ++kt)
; #pragma unroll
;             for (int jj = 0; jj < 4; ++jj) tv[4 * kt + jj] = tb[159 - (32 * (kt >> 1) + 4 * (kt & 1) + jj)];
;         SBAR();
;         float mx = NEGF;
; #pragma unroll
;         for (int kt = 0; kt < 10; ++kt)
; #pragma unroll
;             for (int jj = 0; jj < 4; ++jj) {
;                 const int c = 32 * (kt >> 1) + 4 * (kt & 1) + jj;
;                 float v = S[kt][jj] * 0.125f + tv[4 * kt + jj];
;                 if ((kt >> 1) == 0) v = (L - c <= 128) ? v : NEGF;
;                 if ((kt >> 1) == 4) v = (L - c >= 0) ? v : NEGF;
	global_load_dwordx4 v[56:59], v[0:1], off
	global_load_dwordx4 v[60:63], v[2:3], off
	v_max_i32_e32 v0, 0xffffffc0, v12
	v_add_u32_e32 v0, 64, v0
	v_max_i32_e32 v2, 0xffffffb8, v12
	v_mul_lo_u32 v192, v0, s27
	v_add_u32_e32 v2, 0x48, v2
	v_lshl_add_u64 v[0:1], v[8:9], 0, v[192:193]
	v_mul_lo_u32 v192, v2, s27
	v_lshl_add_u64 v[2:3], v[8:9], 0, v[192:193]
	global_load_dwordx4 v[32:35], v[0:1], off
	global_load_dwordx4 v[36:39], v[2:3], off
	v_max_i32_e32 v0, 0xffffffb0, v12
	v_add_u32_e32 v0, 0x50, v0
	v_max_i32_e32 v2, 0xffffffa8, v12
	v_mul_lo_u32 v192, v0, s27
	v_add_u32_e32 v2, 0x58, v2
	v_lshl_add_u64 v[0:1], v[8:9], 0, v[192:193]
	v_mul_lo_u32 v192, v2, s27
	v_lshl_add_u64 v[2:3], v[8:9], 0, v[192:193]
	global_load_dwordx4 v[40:43], v[0:1], off
	global_load_dwordx4 v[44:47], v[2:3], off
	v_max_i32_e32 v0, 0xffffffa0, v12
	v_add_u32_e32 v0, 0x60, v0
	v_max_i32_e32 v2, 0xffffff98, v12
	v_mul_lo_u32 v192, v0, s27
	v_add_u32_e32 v2, 0x68, v2
	v_lshl_add_u64 v[0:1], v[8:9], 0, v[192:193]
	v_mul_lo_u32 v192, v2, s27
	v_lshl_add_u64 v[2:3], v[8:9], 0, v[192:193]
	global_load_dwordx4 v[16:19], v[0:1], off
	global_load_dwordx4 v[20:23], v[2:3], off
	v_max_i32_e32 v0, 0xffffff90, v12
	v_add_u32_e32 v0, 0x70, v0
	v_max_i32_e32 v2, 0xffffff88, v12
	v_mul_lo_u32 v192, v0, s27
	v_add_u32_e32 v2, 0x78, v2
	v_lshl_add_u64 v[0:1], v[8:9], 0, v[192:193]
	v_mul_lo_u32 v192, v2, s27
	v_lshl_add_u64 v[2:3], v[8:9], 0, v[192:193]
	global_load_dwordx4 v[24:27], v[0:1], off
	global_load_dwordx4 v[28:31], v[2:3], off
	v_max_i32_e32 v0, 0xffffff80, v12
	v_add_u32_e32 v0, 0x80, v0
	v_max_i32_e32 v2, 0xffffff78, v12
	v_mul_lo_u32 v192, v0, s27
	v_add_u32_e32 v2, 0x88, v2
	v_add_u32_e32 v10, s24, v139
	v_lshl_add_u64 v[0:1], v[8:9], 0, v[192:193]
	v_mul_lo_u32 v192, v2, s27
	v_max_i32_e32 v10, 0, v10
	v_max_i32_e32 v12, 0xffffff68, v12
	v_lshl_add_u64 v[4:5], v[8:9], 0, v[192:193]
	v_mul_lo_u32 v192, s27, v10
	v_add_u32_e32 v12, 0x98, v12
	v_lshl_add_u64 v[10:11], v[8:9], 0, v[192:193]
	v_mul_lo_u32 v192, v12, s27
	v_lshl_add_u64 v[12:13], v[8:9], 0, v[192:193]
	global_load_dwordx4 v[0:3], v[0:1], off
	s_nop 0
	global_load_dwordx4 v[4:7], v[4:5], off
	s_nop 0
	global_load_dwordx4 v[8:11], v[10:11], off
	s_nop 0
	global_load_dwordx4 v[12:15], v[12:13], off
	s_waitcnt vmcnt(36)
	ds_write_b128 v206, v[146:149] offset:2240
	ds_write_b128 v206, v[150:153] offset:2816
	ds_write_b128 v206, v[154:157] offset:3392
	ds_write_b128 v206, v[158:161] offset:3968
	ds_read_b128 v[146:149], v207 offset:2240
	ds_read_b128 v[150:153], v207 offset:2304
	ds_read_b128 v[154:157], v207 offset:4544
	ds_read_b128 v[158:161], v207 offset:4608
	s_waitcnt lgkmcnt(0)
	s_waitcnt vmcnt(39)
	v_mfma_f32_16x16x32_bf16 v[146:149], v[146:149], v[84:87], 0
	s_mulk_i32 s26, 0x2c0
	v_add_u32_e32 v186, s26, v135
	ds_read2_b32 v[182:183], v186 offset0:173 offset1:176
	s_waitcnt vmcnt(38)
	v_mfma_f32_16x16x32_bf16 v[146:149], v[150:153], v[80:83], v[146:149]
	s_waitcnt vmcnt(37)
	v_mfma_f32_16x16x32_bf16 v[150:153], v[154:157], v[84:87], 0
	s_waitcnt vmcnt(36)
	v_mfma_f32_16x16x32_bf16 v[154:157], v[158:161], v[80:83], v[150:153]
	s_waitcnt lgkmcnt(0)
	s_nop 2
	v_fmamk_f32 v146, v146, 0x3e000000, v183
	v_fmac_f32_e32 v182, 0x3e000000, v149
	v_cndmask_b32_e64 v146, v237, v146, s[38:39]
	s_waitcnt vmcnt(32)
	ds_write_b128 v206, v[162:165] offset:2240
	ds_write_b128 v206, v[166:169] offset:2816
	ds_write_b128 v206, v[170:173] offset:3392
	ds_write_b128 v206, v[174:177] offset:3968
	ds_read_b128 v[162:165], v207 offset:2240
	ds_read_b128 v[166:169], v207 offset:2304
	ds_read_b128 v[170:173], v207 offset:4544
	ds_read_b128 v[174:177], v207 offset:4608
	s_waitcnt lgkmcnt(0)
	s_waitcnt vmcnt(35)
	v_mfma_f32_16x16x32_bf16 v[150:153], v[162:165], v[84:87], 0
	ds_read2_b32 v[162:163], v186 offset0:174 offset1:175
	v_mov_b32_e32 v164, v147
	v_mov_b32_e32 v165, v148
	s_waitcnt vmcnt(34)
	v_mfma_f32_16x16x32_bf16 v[158:161], v[166:169], v[80:83], v[150:153]
	ds_read2_b32 v[184:185], v186 offset0:169 offset1:170
	s_nop 1
	ds_read2_b32 v[150:151], v186 offset0:171 offset1:172
	s_waitcnt lgkmcnt(2)
	v_pk_fma_f32 v[152:153], v[164:165], s[80:81], v[162:163] op_sel:[0,0,1] op_sel_hi:[1,0,0]
	v_cndmask_b32_e64 v149, v237, v182, s[46:47]
	s_waitcnt vmcnt(33)
	v_mfma_f32_16x16x32_bf16 v[162:165], v[170:173], v[84:87], 0
	s_waitcnt lgkmcnt(1)
	v_fmac_f32_e32 v184, 0x3e000000, v157
	s_waitcnt lgkmcnt(0)
	v_pk_fma_f32 v[150:151], v[154:155], s[80:81], v[150:151] op_sel:[0,0,1] op_sel_hi:[1,0,0]
	v_cndmask_b32_e64 v147, v237, v153, s[40:41]
	s_waitcnt vmcnt(28)
	ds_write_b128 v206, v[178:181] offset:2240
	ds_write_b128 v206, v[128:131] offset:2816
	ds_write_b128 v206, v[124:127] offset:3392
	ds_write_b128 v206, v[120:123] offset:3968
	ds_read_b128 v[178:181], v207 offset:2240
	ds_read_b128 v[128:131], v207 offset:2304
	ds_read_b128 v[124:127], v207 offset:4544
	ds_read_b128 v[120:123], v207 offset:4608
	s_waitcnt lgkmcnt(0)
	s_waitcnt vmcnt(31)
	v_mfma_f32_16x16x32_bf16 v[166:169], v[178:181], v[84:87], 0
	v_cndmask_b32_e64 v148, v237, v151, s[50:51]
	v_cndmask_b32_e64 v151, v237, v150, s[44:45]
	v_fmamk_f32 v150, v156, 0x3e000000, v185
	v_mfma_f32_16x16x32_bf16 v[162:165], v[174:177], v[80:83], v[162:165]
	v_cndmask_b32_e64 v152, v237, v152, s[42:43]
	v_cndmask_b32_e64 v150, v237, v150, s[48:49]
	s_waitcnt vmcnt(30)
	v_mfma_f32_16x16x32_bf16 v[154:157], v[128:131], v[80:83], v[166:169]
	ds_read2_b32 v[130:131], v186 offset0:143 offset1:144
	ds_read2_b32 v[170:171], v186 offset0:141 offset1:142
	ds_read2_b32 v[172:173], v186 offset0:139 offset1:140
	ds_read2_b32 v[174:175], v186 offset0:137 offset1:138
	v_cndmask_b32_e64 v128, v237, v184, s[52:53]
	s_waitcnt vmcnt(29)
; #define GAS __attribute__((address_space(1)))
; #define LAS __attribute__((address_space(3)))
; __device__ __forceinline__ f32x4 mfma16(bf16x8 a, bf16x8 b, f32x4 c) { return __builtin_amdgcn_mfma_f32_16x16x32_bf16(a, b, c, 0, 0, 0); }
; #define SBAR() __builtin_amdgcn_sched_barrier(0)
; #define SBAR() __builtin_amdgcn_sched_barrier(0)
; __device__ __forceinline__ void attnA_unit(const Ctx& C, int unit) {
;     ...
;         bf16x8 kf[10][2];
; #pragma unroll
;         for (int kt = 0; kt < 10; ++kt) { int ks = klane + 32 * (kt >> 1) + 4 * (kt & 1); ks = ks < 0 ? 0 : ks;
;             const unsigned off = (unsigned)ks * rstride + kcol; kf[kt][0] = *(const GAS bf16x8*)(Zg + off); kf[kt][1] = *(const GAS bf16x8*)(Zg + off + 64); }
;         v4u vreg[5][4];
;         { const int vl = kbase + (lane >> 3); const unsigned vcol = rbase + (VA + head * 64 + (lane & 7) * 8) * 2;
; #pragma unroll
;           for (int s5 = 0; s5 < 5; ++s5)
; #pragma unroll
;             for (int i = 0; i < 4; ++i) { int ks = vl + 32 * s5 + 8 * i; ks = ks < 0 ? 0 : ks; vreg[s5][i] = *(const GAS v4u*)(Zg + (unsigned)ks * rstride + vcol); } }
;         SBAR();
;         f32x4 S[10];
; #pragma unroll
;         for (int kt = 0; kt < 10; ++kt) { f32x4 a = mfma16(kf[kt][0], q0, (f32x4){0.f, 0.f, 0.f, 0.f}); S[kt] = mfma16(kf[kt][1], q1, a); }
;         const LAS float* tb = biasT + grp * 176 + 16 + L - 159;
;         const int kneg = kbase + 8 * g;
;         const bool anyneg = kbase < 0;
;         float tv[40];
; #pragma unroll
;         for (int kt = 0; kt < 10; ++kt)
; #pragma unroll
;             for (int jj = 0; jj < 4; ++jj) tv[4 * kt + jj] = tb[159 - (32 * (kt >> 1) + 4 * (kt & 1) + jj)];
;         SBAR();
;         float mx = NEGF;
; #pragma unroll
;         for (int kt = 0; kt < 10; ++kt)
; #pragma unroll
;             for (int jj = 0; jj < 4; ++jj) {
;                 const int c = 32 * (kt >> 1) + 4 * (kt & 1) + jj;
;                 float v = S[kt][jj] * 0.125f + tv[4 * kt + jj];
;                 if ((kt >> 1) == 0) v = (L - c <= 128) ? v : NEGF;
;                 if ((kt >> 1) == 4) v = (L - c >= 0) ? v : NEGF;
	v_mfma_f32_16x16x32_bf16 v[166:169], v[124:127], v[84:87], 0
	s_waitcnt lgkmcnt(3)
	v_pk_fma_f32 v[126:127], v[158:159], s[80:81], v[130:131] op_sel:[0,0,1] op_sel_hi:[1,0,0]
	s_waitcnt lgkmcnt(2)
	v_pk_fma_f32 v[124:125], v[160:161], s[80:81], v[170:171] op_sel:[0,0,1] op_sel_hi:[1,0,0]
	ds_read2_b32 v[130:131], v186 offset0:111 offset1:112
	s_waitcnt vmcnt(28)
	v_mfma_f32_16x16x32_bf16 v[158:161], v[120:123], v[80:83], v[166:169]
	s_waitcnt lgkmcnt(2)
	v_pk_fma_f32 v[122:123], v[162:163], s[80:81], v[172:173] op_sel:[0,0,1] op_sel_hi:[1,0,0]
	s_waitcnt lgkmcnt(1)
	v_pk_fma_f32 v[120:121], v[164:165], s[80:81], v[174:175] op_sel:[0,0,1] op_sel_hi:[1,0,0]
	s_waitcnt vmcnt(24)
	ds_write_b128 v206, v[116:119] offset:2240
	ds_write_b128 v206, v[112:115] offset:2816
	ds_write_b128 v206, v[108:111] offset:3392
	ds_write_b128 v206, v[100:103] offset:3968
	ds_read_b128 v[116:119], v207 offset:2240
	ds_read_b128 v[112:115], v207 offset:2304
	ds_read_b128 v[108:111], v207 offset:4544
	ds_read_b128 v[100:103], v207 offset:4608
	s_waitcnt lgkmcnt(0)
	s_waitcnt vmcnt(27)
	v_mfma_f32_16x16x32_bf16 v[162:165], v[116:119], v[84:87], 0
	ds_read2_b32 v[116:117], v186 offset0:109 offset1:110
	ds_read2_b32 v[166:167], v186 offset0:107 offset1:108
	ds_read2_b32 v[168:169], v186 offset0:105 offset1:106
	s_waitcnt lgkmcnt(3)
	v_pk_fma_f32 v[118:119], v[154:155], s[80:81], v[130:131] op_sel:[0,0,1] op_sel_hi:[1,0,0]
	s_waitcnt lgkmcnt(2)
	v_pk_fma_f32 v[116:117], v[156:157], s[80:81], v[116:117] op_sel:[0,0,1] op_sel_hi:[1,0,0]
	s_waitcnt vmcnt(25)
	v_mfma_f32_16x16x32_bf16 v[108:111], v[108:111], v[84:87], 0
	v_mfma_f32_16x16x32_bf16 v[162:165], v[112:115], v[80:83], v[162:165]
	s_waitcnt lgkmcnt(1)
	v_pk_fma_f32 v[114:115], v[158:159], s[80:81], v[166:167] op_sel:[0,0,1] op_sel_hi:[1,0,0]
	s_waitcnt lgkmcnt(0)
	v_pk_fma_f32 v[112:113], v[160:161], s[80:81], v[168:169] op_sel:[0,0,1] op_sel_hi:[1,0,0]
	ds_read2_b32 v[130:131], v186 offset0:79 offset1:80
	ds_read2_b32 v[158:159], v186 offset0:77 offset1:78
	ds_read2_b32 v[160:161], v186 offset0:75 offset1:76
	ds_read2_b32 v[166:167], v186 offset0:73 offset1:74
	s_waitcnt vmcnt(24)
	v_mfma_f32_16x16x32_bf16 v[154:157], v[100:103], v[80:83], v[108:111]
	s_waitcnt vmcnt(20)
	ds_write_b128 v206, v[104:107] offset:2240
	ds_write_b128 v206, v[96:99] offset:2816
	ds_write_b128 v206, v[92:95] offset:3392
	ds_write_b128 v206, v[88:91] offset:3968
	ds_read_b128 v[104:107], v207 offset:2240
	ds_read_b128 v[96:99], v207 offset:2304
	ds_read_b128 v[92:95], v207 offset:4544
	ds_read_b128 v[88:91], v207 offset:4608
	s_waitcnt lgkmcnt(0)
	s_waitcnt vmcnt(23)
	v_mfma_f32_16x16x32_bf16 v[104:107], v[104:107], v[84:87], 0
	s_waitcnt lgkmcnt(3)
	v_pk_fma_f32 v[110:111], v[162:163], s[80:81], v[130:131] op_sel:[0,0,1] op_sel_hi:[1,0,0]
	s_waitcnt lgkmcnt(1)
	s_nop 2
	v_pk_fma_f32 v[102:103], v[154:155], s[80:81], v[160:161] op_sel:[0,0,1] op_sel_hi:[1,0,0]
	ds_read2_b32 v[130:131], v186 offset0:47 offset1:48
	ds_read2_b32 v[154:155], v186 offset0:45 offset1:46
	s_waitcnt vmcnt(22)
	v_mfma_f32_16x16x32_bf16 v[96:99], v[96:99], v[80:83], v[104:107]
	v_fma_f32 v108, v164, s80, v159
	v_fma_f32 v109, v165, s80, v158
	s_waitcnt lgkmcnt(2)
	v_pk_fma_f32 v[100:101], v[156:157], s[80:81], v[166:167] op_sel:[0,0,1] op_sel_hi:[1,0,0]
	s_waitcnt vmcnt(21)
	v_mfma_f32_16x16x32_bf16 v[92:95], v[92:95], v[84:87], 0
	s_waitcnt vmcnt(20)
	v_mfma_f32_16x16x32_bf16 v[86:89], v[88:91], v[80:83], v[92:95]
	s_waitcnt lgkmcnt(1)
	v_pk_fma_f32 v[104:105], v[96:97], s[80:81], v[130:131] op_sel:[0,0,1] op_sel_hi:[1,0,0]
	s_waitcnt lgkmcnt(0)
	v_pk_fma_f32 v[98:99], v[98:99], s[80:81], v[154:155] op_sel:[0,0,1] op_sel_hi:[1,0,0]
	v_cndmask_b32_e64 v96, v105, v237, s[38:39]
	v_cndmask_b32_e64 v97, v104, v237, s[54:55]
	ds_read2_b32 v[104:105], v186 offset0:43 offset1:44
	v_cndmask_b32_e64 v84, v99, v237, s[40:41]
	v_cndmask_b32_e64 v85, v98, v237, s[42:43]
	ds_read2_b32 v[98:99], v186 offset0:41 offset1:42
	s_waitcnt lgkmcnt(1)
	v_pk_fma_f32 v[80:81], v[86:87], s[80:81], v[104:105] op_sel:[0,0,1] op_sel_hi:[1,0,0]
	s_nop 0
	v_cndmask_b32_e64 v82, v81, v237, s[44:45]
	v_cndmask_b32_e64 v83, v80, v237, s[46:47]
	s_waitcnt lgkmcnt(0)
	v_pk_fma_f32 v[86:87], v[88:89], s[80:81], v[98:99] op_sel:[0,0,1] op_sel_hi:[1,0,0]
	s_cmpk_gt_i32 s24, 0x8f
	v_cndmask_b32_e64 v80, v87, v237, s[48:49]
	v_cndmask_b32_e64 v86, v86, v237, s[50:51]
	s_cbranch_scc1 .LBB0_567
; __device__ __forceinline__ void attnA_unit(const Ctx& C, int unit) {
;     ...
;         if (anyneg) {
; #pragma unroll
;             for (int kt = 0; kt < 10; ++kt)
; #pragma unroll
;                 for (int jj = 0; jj < 4; ++jj) { const int c = 32 * (kt >> 1) + 4 * (kt & 1) + jj; S[kt][jj] = (kneg + c >= 0) ? S[kt][jj] : NEGF; }
;         }
	v_add_u32_e32 v81, s25, v134
	v_cmp_lt_i32_e64 s[56:57], -1, v81
	s_movk_i32 s24, 0xffdf
	s_nop 0
	v_cndmask_b32_e64 v146, v237, v146, s[56:57]
	v_cmp_lt_i32_e64 s[56:57], -2, v81
	s_nop 1
	v_cndmask_b32_e64 v152, v237, v152, s[56:57]
	v_cmp_lt_i32_e64 s[56:57], -3, v81
	s_nop 1
	v_cndmask_b32_e64 v147, v237, v147, s[56:57]
	v_cmp_lt_i32_e64 s[56:57], -4, v81
	s_nop 1
	v_cndmask_b32_e64 v149, v237, v149, s[56:57]
	v_cmp_lt_i32_e64 s[56:57], -5, v81
	s_nop 1
	v_cndmask_b32_e64 v151, v237, v151, s[56:57]
	v_cmp_lt_i32_e64 s[56:57], -6, v81
	s_nop 1
	v_cndmask_b32_e64 v148, v237, v148, s[56:57]
	v_cmp_lt_i32_e64 s[56:57], -7, v81
	s_nop 1
	v_cndmask_b32_e64 v150, v237, v150, s[56:57]
	v_cmp_lt_i32_e64 s[56:57], -8, v81
	s_nop 1
	v_cndmask_b32_e64 v128, v237, v128, s[56:57]
	v_cmp_lt_i32_e64 s[56:57], s24, v81
	s_movk_i32 s24, 0xffde
	s_nop 0
	v_cndmask_b32_e64 v126, v237, v126, s[56:57]
	v_cmp_lt_i32_e64 s[56:57], s24, v81
	s_movk_i32 s24, 0xffdd
	s_nop 0
	v_cndmask_b32_e64 v127, v237, v127, s[56:57]
	v_cmp_lt_i32_e64 s[56:57], s24, v81
	s_movk_i32 s24, 0xffdc
	s_nop 0
	v_cndmask_b32_e64 v124, v237, v124, s[56:57]
	v_cmp_lt_i32_e64 s[56:57], s24, v81
	s_movk_i32 s24, 0xffdb
	s_nop 0
	v_cndmask_b32_e64 v125, v237, v125, s[56:57]
	v_cmp_lt_i32_e64 s[56:57], s24, v81
	s_movk_i32 s24, 0xffda
	s_nop 0
	v_cndmask_b32_e64 v122, v237, v122, s[56:57]
	v_cmp_lt_i32_e64 s[56:57], s24, v81
	s_movk_i32 s24, 0xffd9
	s_nop 0
	v_cndmask_b32_e64 v123, v237, v123, s[56:57]
	v_cmp_lt_i32_e64 s[56:57], s24, v81
	s_movk_i32 s24, 0xffd8
	s_nop 0
	v_cndmask_b32_e64 v120, v237, v120, s[56:57]
	v_cmp_lt_i32_e64 s[56:57], s24, v81
	s_movk_i32 s24, 0xffbf
	s_nop 0
	v_cndmask_b32_e64 v121, v237, v121, s[56:57]
	v_cmp_lt_i32_e64 s[56:57], s24, v81
	s_movk_i32 s24, 0xffbe
	s_nop 0
	v_cndmask_b32_e64 v118, v237, v118, s[56:57]
	v_cmp_lt_i32_e64 s[56:57], s24, v81
	s_movk_i32 s24, 0xffbd
	s_nop 0
	v_cndmask_b32_e64 v119, v237, v119, s[56:57]
	v_cmp_lt_i32_e64 s[56:57], s24, v81
	s_movk_i32 s24, 0xffbc
	s_nop 0
	v_cndmask_b32_e64 v116, v237, v116, s[56:57]
	v_cmp_lt_i32_e64 s[56:57], s24, v81
	s_movk_i32 s24, 0xffbb
	s_nop 0
	v_cndmask_b32_e64 v117, v237, v117, s[56:57]
	v_cmp_lt_i32_e64 s[56:57], s24, v81
	s_movk_i32 s24, 0xffba
	s_nop 0
	v_cndmask_b32_e64 v114, v237, v114, s[56:57]
	v_cmp_lt_i32_e64 s[56:57], s24, v81
	s_movk_i32 s24, 0xffb9
	s_nop 0
	v_cndmask_b32_e64 v115, v237, v115, s[56:57]
	v_cmp_lt_i32_e64 s[56:57], s24, v81
	s_movk_i32 s24, 0xffb8
	s_nop 0
	v_cndmask_b32_e64 v112, v237, v112, s[56:57]
	v_cmp_lt_i32_e64 s[56:57], s24, v81
	s_movk_i32 s24, 0xff9f
	s_nop 0
	v_cndmask_b32_e64 v113, v237, v113, s[56:57]
	v_cmp_lt_i32_e64 s[56:57], s24, v81
	s_movk_i32 s24, 0xff9e
	s_nop 0
	v_cndmask_b32_e64 v110, v237, v110, s[56:57]
	v_cmp_lt_i32_e64 s[56:57], s24, v81
	s_movk_i32 s24, 0xff9d
	s_nop 0
	v_cndmask_b32_e64 v111, v237, v111, s[56:57]
	v_cmp_lt_i32_e64 s[56:57], s24, v81
	s_movk_i32 s24, 0xff9c
	s_nop 0
	v_cndmask_b32_e64 v108, v237, v108, s[56:57]
	v_cmp_lt_i32_e64 s[56:57], s24, v81
	s_movk_i32 s24, 0xff9b
	s_nop 0
	v_cndmask_b32_e64 v109, v237, v109, s[56:57]
	v_cmp_lt_i32_e64 s[56:57], s24, v81
	s_movk_i32 s24, 0xff9a
	s_nop 0
	v_cndmask_b32_e64 v102, v237, v102, s[56:57]
	v_cmp_lt_i32_e64 s[56:57], s24, v81
	s_movk_i32 s24, 0xff99
	s_nop 0
	v_cndmask_b32_e64 v103, v237, v103, s[56:57]
	v_cmp_lt_i32_e64 s[56:57], s24, v81
	s_movk_i32 s24, 0xff98
	s_nop 0
	v_cndmask_b32_e64 v100, v237, v100, s[56:57]
	v_cmp_lt_i32_e64 s[56:57], s24, v81
	s_movk_i32 s24, 0xff7f
	s_nop 0
	v_cndmask_b32_e64 v101, v237, v101, s[56:57]
	v_cmp_lt_i32_e64 s[56:57], s24, v81
	s_movk_i32 s24, 0xff7e
	s_nop 0
	v_cndmask_b32_e64 v97, v237, v97, s[56:57]
	v_cmp_lt_i32_e64 s[56:57], s24, v81
	s_movk_i32 s24, 0xff7d
	s_nop 0
	v_cndmask_b32_e64 v96, v237, v96, s[56:57]
	v_cmp_lt_i32_e64 s[56:57], s24, v81
	s_movk_i32 s24, 0xff7b
	s_nop 0
	v_cndmask_b32_e64 v85, v237, v85, s[56:57]
	v_cmp_lt_i32_e64 s[56:57], s6, v81
	s_nop 1
	v_cndmask_b32_e64 v84, v237, v84, s[56:57]
	v_cmp_lt_i32_e64 s[56:57], s24, v81
	s_movk_i32 s24, 0xff7a
	s_nop 0
	v_cndmask_b32_e64 v83, v237, v83, s[56:57]
	v_cmp_lt_i32_e64 s[56:57], s24, v81
	s_movk_i32 s24, 0xff79
	s_nop 0
	v_cndmask_b32_e64 v82, v237, v82, s[56:57]
	v_cmp_lt_i32_e64 s[56:57], s24, v81
	s_movk_i32 s24, 0xff78
	s_nop 0
	v_cndmask_b32_e64 v86, v237, v86, s[56:57]
	v_cmp_lt_i32_e64 s[56:57], s24, v81
	s_nop 1
	v_cndmask_b32_e64 v80, v237, v80, s[56:57]
